# per-head LRU sync: counter polled at queue exit without waiting, tested at the carry-scan entry (one barrier instead of two plus a round trip)
# baseline (speedup 1.0000x reference)
.LBB0_431:
	s_and_saveexec_b64 s[100:101], s[56:57]
	s_cbranch_execz .Lhw_done
	s_and_b32 s98, s2, 15
	s_lshl_b32 s99, s96, 4
	s_add_i32 s98, s98, s99
	s_lshl_b32 s98, s98, 2
	s_add_u32 s98, s98, 0x16370d80
	s_add_u32 s98, s68, s98
	s_addc_u32 s99, s69, 0
	v_mov_b32_e32 v246, 0
	global_load_dword v246, v246, s[98:99] sc1
.Lhw_done:
	s_or_b64 exec, exec, s[100:101]
	s_mul_i32 s0, s96, 5
	s_add_i32 s4, s0, 5
	s_branch .LBB0_577
	s_mul_i32 s0, s96, 5
	s_add_i32 s4, s0, 4
	s_cmp_lt_i32 s4, s71
	s_cselect_b64 s[0:1], -1, 0
	s_and_b64 s[6:7], s[28:29], s[0:1]
	s_andn2_b64 vcc, exec, s[6:7]
	s_cbranch_vccnz .LBB0_497
	v_readlane_b32 s6, v244, 18
	v_readlane_b32 s7, v244, 19
	s_andn2_b64 vcc, exec, s[6:7]
	s_cbranch_vccnz .LBB0_444
	s_barrier
	s_mov_b64 s[40:41], exec
	v_readlane_b32 s6, v242, 6
	v_readlane_b32 s7, v242, 7
	s_and_b64 s[6:7], s[40:41], s[6:7]
	s_mov_b64 exec, s[6:7]
	s_cbranch_execz .LBB0_443
	v_readlane_b32 s6, v244, 0
	v_readlane_b32 s7, v244, 1
	buffer_wbl2 sc1
	s_waitcnt vmcnt(0)
	s_load_dwordx2 s[42:43], s[6:7], 0x58
	s_mov_b64 s[44:45], exec
	v_mbcnt_lo_u32_b32 v1, s44, 0
	v_mbcnt_hi_u32_b32 v1, s45, v1
	v_cmp_eq_u32_e32 vcc, 0, v1
	s_waitcnt lgkmcnt(0)
	global_load_dword v0, v145, s[42:43] offset:40
	s_and_saveexec_b64 s[46:47], vcc
	s_cbranch_execz .LBB0_436
	s_bcnt1_i32_b64 s5, s[44:45]
	v_mov_b32_e32 v2, s5
	global_atomic_add v2, v145, v2, s[42:43] offset:32 sc0

.Lcf_entry:
	s_and_saveexec_b64 s[100:101], s[56:57]
	s_cbranch_execz .Lhw2_x
	v_cmp_gt_u32_e32 vcc, 16, v246
	s_cbranch_vccz .Lhw2_x
	v_readlane_b32 s98, v242, 47
	s_nop 3
	s_cmp_eq_u32 s98, 0
	s_cselect_b32 s99, 0, 64
	s_and_b32 s98, s2, 15
	s_lshl_b32 s98, s98, 2
	s_add_u32 s98, s98, s99
	s_add_u32 s98, s98, 0x16370d80
	s_add_u32 s98, s68, s98
	s_addc_u32 s99, s69, 0
	v_mov_b32_e32 v247, 0

.Lhw2_x:
	s_or_b64 exec, exec, s[100:101]
	s_barrier
	v_and_b32_e32 v23, 63, v175
	s_and_b32 s98, s2, 15
	s_lshl_b32 s98, s98, 9
	v_lshl_add_u32 v20, v23, 3, s98
	s_lshr_b32 s98, s98, 1
	v_lshl_add_u32 v21, v23, 2, s98
	v_lshlrev_b32_e32 v22, 3, v23
	v_add_u32_e32 v22, 0x11c80, v22
	s_and_b64 s[100:101], s[10:11], exec
	s_cselect_b32 s99, 0, 2
	s_lshr_b32 s100, s2, 4
	s_add_i32 s99, s99, s100
	s_and_b32 s99, s99, 15
	v_lshrrev_b32_e32 v23, 6, v175
	s_nop 1
	v_readfirstlane_b32 s98, v23
	s_nop 3
	s_cmp_eq_u32 s98, 1
	s_cbranch_scc1 .Lcf_var_1
	s_cmp_eq_u32 s98, 2
	s_cbranch_scc1 .Lcf_var_2
	s_cmp_eq_u32 s98, 3
	s_cbranch_scc1 .Lcf_var_3
	s_cmp_eq_u32 s98, 4
	s_cbranch_scc1 .Lcf_var_4
	s_cmp_eq_u32 s98, 5
	s_cbranch_scc1 .Lcf_var_5
	s_cmp_eq_u32 s98, 6
	s_cbranch_scc1 .Lcf_var_6
	s_cmp_eq_u32 s98, 7
	s_cbranch_scc1 .Lcf_var_7
